# up-projection epilogue (causal conv3 + silu gate) rewritten by hand: sigmoid scale folded into the taps, packed FMAs on accumulator pairs, scalar store addressing, taps prefetched at tile start, histo
# speedup vs baseline: 1.0772x; 1.0090x over previous
;     __device__ __forceinline__ void operator()(const f32x4 (&acc)[2][2][4][2], const Unit& u, int wr, int wc, int fr, int fq) const {
;         const int lane = threadIdx.x & 63;
;         const int j0 = 128 * u.pn + 32 * wc + 2 * fr;
;         float wa[2][3], wb[2][3], ba[2], bb[2];
;         {
;             f32x2_t ta[3], tb[3];
; #pragma unroll
;             for (int k = 0; k < 3; ++k) { ta[k] = *(const f32x2_t*)(cw + k * NUP + j0); tb[k] = *(const f32x2_t*)(cw + k * NUP + DFF + j0); }
;             const f32x2_t tba = *(const f32x2_t*)(cb + j0), tbb = *(const f32x2_t*)(cb + DFF + j0);
; template <class Epi, class Sched, bool ALIGN_EPI = false, bool SP2 = false>
; __device__ __forceinline__ void gemm_phase(PG8_LAS unsigned char* lds, const Gemm g, const Sched& S, const Epi& E) {
;     ...
;         for (int a = 0; a < 2; ++a)
; #pragma unroll
;             for (int b = 0; b < 2; ++b)
; #pragma unroll
;                 for (int m = 0; m < 4; ++m)
; #pragma unroll
;                     for (int n = 0; n < 2; ++n) acc[a][b][m][n] = (f32x4){0.f, 0.f, 0.f, 0.f};
.LBB0_885:
	v_lshrrev_b32_e32 v237, 1, v195
	v_and_b32_e32 v236, 15, v195
	v_and_b32_e32 v237, 0x60, v237
	v_lshl_add_u32 v237, v236, 1, v237
	v_mov_b32_e32 v236, s16
	v_lshl_add_u32 v237, v236, 7, v237
	v_lshlrev_b32_e32 v237, 2, v237
	global_load_dwordx2 v[238:239], v237, s[20:21]
	global_load_dwordx2 v[240:241], v237, s[44:45]
	global_load_dwordx2 v[242:243], v237, s[48:49]
	global_load_dwordx2 v[244:245], v237, s[42:43]
	global_load_dwordx2 v[246:247], v237, s[46:47]
	global_load_dwordx2 v[248:249], v237, s[50:51]
	global_load_dwordx2 v[250:251], v237, s[22:23]
	global_load_dwordx2 v[252:253], v237, s[52:53]
	s_ashr_i32 s69, s68, 31
	s_lshl_b64 s[70:71], s[68:69], 19
	s_add_u32 s70, s31, s70
	s_addc_u32 s71, s35, s71
	s_and_b64 s[72:73], s[14:15], exec
	s_cselect_b32 s17, s71, s77
	s_cselect_b32 s19, s70, s76
	s_ashr_i32 s67, s66, 31
	s_lshl_b64 s[72:73], s[66:67], 19
	s_add_u32 s72, s89, s72
	s_addc_u32 s73, s90, s73
	s_and_b64 s[80:81], s[14:15], exec
	s_cselect_b32 s67, s73, s79
	s_cselect_b32 s69, s72, s78
	s_add_u32 s76, s76, 0x40080
	s_addc_u32 s77, s77, 0
	s_add_u32 s75, s78, 0x100
	v_mov_b32_e32 v8, 0
	s_addc_u32 vcc_lo, s79, 0
	s_mov_b32 vcc_hi, -2
	v_mov_b32_e32 v9, v8
	v_mov_b32_e32 v10, v8
	v_mov_b32_e32 v11, v8
	v_mov_b32_e32 v4, v8
	v_mov_b32_e32 v5, v8
	v_mov_b32_e32 v6, v8
	v_mov_b32_e32 v7, v8
	v_mov_b32_e32 v16, v8
	v_mov_b32_e32 v17, v8
	v_mov_b32_e32 v18, v8
	v_mov_b32_e32 v19, v8
	v_mov_b32_e32 v24, v8
	v_mov_b32_e32 v25, v8
	v_mov_b32_e32 v26, v8
	v_mov_b32_e32 v27, v8
	v_mov_b32_e32 v32, v8
	v_mov_b32_e32 v33, v8
	v_mov_b32_e32 v34, v8
	v_mov_b32_e32 v35, v8
	v_mov_b32_e32 v40, v8
	v_mov_b32_e32 v41, v8
	v_mov_b32_e32 v42, v8
	v_mov_b32_e32 v43, v8
	v_mov_b32_e32 v48, v8
	v_mov_b32_e32 v49, v8
	v_mov_b32_e32 v50, v8
	v_mov_b32_e32 v51, v8
	v_mov_b32_e32 v56, v8
	v_mov_b32_e32 v57, v8
	v_mov_b32_e32 v58, v8
	v_mov_b32_e32 v59, v8
	v_mov_b32_e32 v12, v8
	v_mov_b32_e32 v13, v8
	v_mov_b32_e32 v14, v8
	v_mov_b32_e32 v15, v8
	v_mov_b32_e32 v0, v8
	v_mov_b32_e32 v1, v8
	v_mov_b32_e32 v2, v8
	v_mov_b32_e32 v3, v8
	v_mov_b32_e32 v20, v8
	v_mov_b32_e32 v21, v8
	v_mov_b32_e32 v22, v8
	v_mov_b32_e32 v23, v8
	v_mov_b32_e32 v28, v8
	v_mov_b32_e32 v29, v8
	v_mov_b32_e32 v30, v8
	v_mov_b32_e32 v31, v8
	v_mov_b32_e32 v36, v8
	v_mov_b32_e32 v37, v8
	v_mov_b32_e32 v38, v8
	v_mov_b32_e32 v39, v8
	v_mov_b32_e32 v44, v8
	v_mov_b32_e32 v45, v8
	v_mov_b32_e32 v46, v8
	v_mov_b32_e32 v47, v8
	v_mov_b32_e32 v52, v8
	v_mov_b32_e32 v53, v8
	v_mov_b32_e32 v54, v8
	v_mov_b32_e32 v55, v8
	v_mov_b32_e32 v60, v8
	v_mov_b32_e32 v61, v8
	v_mov_b32_e32 v62, v8
	v_mov_b32_e32 v63, v8
	v_mov_b32_e32 v72, v8
	v_mov_b32_e32 v73, v8
	v_mov_b32_e32 v74, v8
	v_mov_b32_e32 v75, v8
	v_mov_b32_e32 v64, v8
	v_mov_b32_e32 v65, v8
	v_mov_b32_e32 v66, v8
	v_mov_b32_e32 v67, v8
	v_mov_b32_e32 v80, v8
	v_mov_b32_e32 v81, v8
	v_mov_b32_e32 v82, v8
	v_mov_b32_e32 v83, v8
	v_mov_b32_e32 v88, v8
	v_mov_b32_e32 v89, v8
	v_mov_b32_e32 v90, v8
	v_mov_b32_e32 v91, v8
	v_mov_b32_e32 v96, v8
	v_mov_b32_e32 v97, v8
	v_mov_b32_e32 v98, v8
	v_mov_b32_e32 v99, v8
	v_mov_b32_e32 v104, v8
	v_mov_b32_e32 v105, v8
	v_mov_b32_e32 v106, v8
	v_mov_b32_e32 v107, v8
	v_mov_b32_e32 v112, v8
	v_mov_b32_e32 v113, v8
	v_mov_b32_e32 v114, v8
	v_mov_b32_e32 v115, v8
	v_mov_b32_e32 v120, v8
	v_mov_b32_e32 v121, v8
	v_mov_b32_e32 v122, v8
	v_mov_b32_e32 v123, v8
	v_mov_b32_e32 v76, v8
	v_mov_b32_e32 v77, v8
	v_mov_b32_e32 v78, v8
	v_mov_b32_e32 v79, v8
	v_mov_b32_e32 v68, v8
	v_mov_b32_e32 v69, v8
	v_mov_b32_e32 v70, v8
	v_mov_b32_e32 v71, v8
	v_mov_b32_e32 v84, v8
	v_mov_b32_e32 v85, v8
	v_mov_b32_e32 v86, v8
	v_mov_b32_e32 v87, v8
	v_mov_b32_e32 v92, v8
	v_mov_b32_e32 v93, v8
	v_mov_b32_e32 v94, v8
	v_mov_b32_e32 v95, v8
	v_mov_b32_e32 v100, v8
	v_mov_b32_e32 v101, v8
	v_mov_b32_e32 v102, v8
	v_mov_b32_e32 v103, v8
	v_mov_b32_e32 v108, v8
	v_mov_b32_e32 v109, v8
	v_mov_b32_e32 v110, v8
	v_mov_b32_e32 v111, v8
	v_mov_b32_e32 v116, v8
	v_mov_b32_e32 v117, v8
	v_mov_b32_e32 v118, v8
	v_mov_b32_e32 v119, v8
	v_mov_b32_e32 v124, v8
	v_mov_b32_e32 v125, v8
	v_mov_b32_e32 v126, v8
	v_mov_b32_e32 v127, v8

;     __device__ __forceinline__ void operator()(const f32x4 (&acc)[2][2][4][2], const Unit& u, int wr, int wc, int fr, int fq) const {
;     ...
;         if (fq == 3) {
; #pragma unroll
;             for (int ai = 0; ai < 2; ++ai)
; #pragma unroll
;                 for (int bj = 0; bj < 2; ++bj)
; #pragma unroll
;                     for (int n = 0; n < 2; ++n) { PG8_LAS float* hp = halo + (((((ai * 2 + wr) * 4 + wc) * 2 + bj) * 2 + n) * 32) + fr; hp[0] = acc[ai][bj][3][n][2]; hp[16] = acc[ai][bj][3][n][3]; }
;         }
;         asm volatile("s_waitcnt lgkmcnt(0)" ::: "memory"); __builtin_amdgcn_s_barrier(); asm volatile("" ::: "memory");
;         const int src = ((lane - 16) & 63) * 4;
; #pragma unroll
;         for (int ai = 0; ai < 2; ++ai) {
;             const int blk = 2 * ai + wr;
; #pragma unroll
;             for (int m = 0; m < 4; ++m) {
;                 float o[2][4];
; #pragma unroll
;                 for (int n = 0; n < 2; ++n) {
;                     const f32x4 Xa = acc[ai][0][m][n], Xb = acc[ai][1][m][n];
;                     float da2, da3, db2, db3;
;                     if (m > 0) { const bool t = (fq == 3); da2 = t ? acc[ai][0][m > 0 ? m - 1 : 0][n][2] : Xa[2]; da3 = t ? acc[ai][0][m > 0 ? m - 1 : 0][n][3] : Xa[3];
;                                  db2 = t ? acc[ai][1][m > 0 ? m - 1 : 0][n][2] : Xb[2]; db3 = t ? acc[ai][1][m > 0 ? m - 1 : 0][n][3] : Xb[3]; }
;                     else { da2 = Xa[2]; da3 = Xa[3]; db2 = Xb[2]; db3 = Xb[3]; }
;                     float Ha2 = __builtin_bit_cast(float, __builtin_amdgcn_ds_bpermute(src, __builtin_bit_cast(int, da2)));
;                     float Ha3 = __builtin_bit_cast(float, __builtin_amdgcn_ds_bpermute(src, __builtin_bit_cast(int, da3)));
;                     float Hb2 = __builtin_bit_cast(float, __builtin_amdgcn_ds_bpermute(src, __builtin_bit_cast(int, db2)));
;                     float Hb3 = __builtin_bit_cast(float, __builtin_amdgcn_ds_bpermute(src, __builtin_bit_cast(int, db3)));
;                     if (m == 0) {
;                         float h2a = 0.f, h3a = 0.f, h2b = 0.f, h3b = 0.f;
;                         if (blk > 0) { const PG8_LAS float* hp = halo + ((((blk - 1) * 4 + wc) * 2 + 0) * 2 + n) * 32 + fr; h2a = hp[0]; h3a = hp[16]; h2b = hp[64]; h3b = hp[80]; }
;                         if (fq == 0) { Ha2 = h2a; Ha3 = h3a; Hb2 = h2b; Hb3 = h3b; }
;                     }
.LBB0_889:
	v_readfirstlane_b32 s19, v195
	v_and_b32_e32 v190, 15, v195
	v_bfe_u32 v191, v195, 4, 2
	s_lshr_b32 s19, s19, 6
	s_and_b32 s24, s19, 3
	s_lshr_b32 s25, s19, 2
	v_lshrrev_b32_e32 v192, 2, v237
	s_lshl_b32 s27, s25, 6
	v_lshl_add_u32 v193, v191, 2, s27
	v_mul_u32_u24_e32 v193, 0x1600, v193
	v_lshl_add_u32 v157, v192, 1, v193
	v_add_u32_e32 v158, 48, v195
	v_and_b32_e32 v158, 63, v158
	v_lshlrev_b32_e32 v158, 2, v158
	s_lshl_b32 s27, s25, 11
	s_lshl_b32 s17, s24, 9
	s_add_i32 s27, s27, s17
	s_add_i32 s27, s27, 0x20400
	v_lshl_add_u32 v159, v190, 2, s27
	v_add_u32_e32 v160, 0xfffff800, v159
	v_mov_b32_e32 v162, 1.0
	v_mov_b32_e32 v163, 1.0
	s_and_saveexec_b64 s[16:17], s[6:7]
	ds_write_b32 v159, v70
	ds_write_b32 v159, v71 offset:64
	ds_write_b32 v159, v78 offset:128
	ds_write_b32 v159, v79 offset:192
	ds_write_b32 v159, v66 offset:256
	ds_write_b32 v159, v67 offset:320
	ds_write_b32 v159, v74 offset:384
	ds_write_b32 v159, v75 offset:448
	ds_write_b32 v159, v2 offset:4096
	ds_write_b32 v159, v3 offset:4160
	ds_write_b32 v159, v14 offset:4224
	ds_write_b32 v159, v15 offset:4288
	ds_write_b32 v159, v6 offset:4352
	ds_write_b32 v159, v7 offset:4416
	s_waitcnt lgkmcnt(13)
	ds_write_b32 v159, v10 offset:4480
	s_waitcnt lgkmcnt(13)
	ds_write_b32 v159, v11 offset:4544
	s_or_b64 exec, exec, s[16:17]
	s_waitcnt lgkmcnt(0)
	s_barrier
	s_cmp_eq_u32 s25, 0
	s_cbranch_scc1 .Lp8_nohalo
	ds_read_b32 v228, v160
	ds_read_b32 v229, v160 offset:64
	ds_read_b32 v230, v160 offset:256
	ds_read_b32 v231, v160 offset:320
	ds_read_b32 v232, v160 offset:128
	ds_read_b32 v233, v160 offset:192
	ds_read_b32 v234, v160 offset:384
	ds_read_b32 v235, v160 offset:448
	s_branch .Lp8_halo_done
.Lp8_nohalo:
	v_mov_b32_e32 v228, 0
	v_mov_b32_e32 v229, 0
	v_mov_b32_e32 v230, 0
	v_mov_b32_e32 v231, 0
	v_mov_b32_e32 v232, 0
	v_mov_b32_e32 v233, 0
	v_mov_b32_e32 v234, 0
	v_mov_b32_e32 v235, 0
.Lp8_halo_done:
	ds_bpermute_b32 v196, v158, v126
	ds_bpermute_b32 v197, v158, v127
	ds_bpermute_b32 v198, v158, v122
	ds_bpermute_b32 v199, v158, v123
	ds_bpermute_b32 v200, v158, v118
	ds_bpermute_b32 v201, v158, v119
	s_waitcnt lgkmcnt(13)
	ds_bpermute_b32 v202, v158, v114
	s_waitcnt lgkmcnt(13)
	ds_bpermute_b32 v203, v158, v115
	v_mul_f32_e32 v238, 0xbfb8aa3b, v238
	v_mul_f32_e32 v239, 0xbfb8aa3b, v239
	v_mul_f32_e32 v244, 0xbf317218, v244
	v_mul_f32_e32 v245, 0xbf317218, v245
	v_mul_f32_e32 v240, 0xbfb8aa3b, v240
	v_mul_f32_e32 v241, 0xbfb8aa3b, v241
	v_mul_f32_e32 v246, 0xbf317218, v246
	v_mul_f32_e32 v247, 0xbf317218, v247
	v_mul_f32_e32 v242, 0xbfb8aa3b, v242
	v_mul_f32_e32 v243, 0xbfb8aa3b, v243
	v_mul_f32_e32 v248, 0xbf317218, v248
	v_mul_f32_e32 v249, 0xbf317218, v249
	v_mul_f32_e32 v250, 0xbfb8aa3b, v250
	v_mul_f32_e32 v251, 0xbfb8aa3b, v251
	v_mul_f32_e32 v252, 0xbf317218, v252
	v_mul_f32_e32 v253, 0xbf317218, v253
	s_mul_i32 s26, s74, 0x16000
	s_add_u32 s26, s87, s26
	s_addc_u32 s27, s88, 0
	s_cmp_eq_u32 s25, 0
	s_cbranch_scc0 .Lp8_side_hi
	s_and_saveexec_b64 s[16:17], s[8:9]
	global_store_dword v237, v124, s[26:27]
	global_store_dword v237, v116, s[26:27] offset:4
	s_add_u32 s26, s26, 0x2c00
	s_addc_u32 s27, s27, 0
	global_store_dword v237, v120, s[26:27]
	global_store_dword v237, v112, s[26:27] offset:4
	s_add_u32 s26, s26, 0x2c00
	s_addc_u32 s27, s27, 0
	global_store_dword v237, v125, s[26:27]
	global_store_dword v237, v117, s[26:27] offset:4
	s_add_u32 s26, s26, 0x2c00
	s_addc_u32 s27, s27, 0
	global_store_dword v237, v121, s[26:27]
	global_store_dword v237, v113, s[26:27] offset:4
	s_add_u32 s26, s26, 0x2c00
	s_addc_u32 s27, s27, 0
	s_or_b64 exec, exec, s[16:17]
	s_branch .Lp8_side_done
.Lp8_side_hi:
	s_add_u32 s26, s26, 0xb000
	s_addc_u32 s27, s27, 0
	s_and_saveexec_b64 s[16:17], s[6:7]
	global_store_dword v237, v2, s[26:27]
	global_store_dword v237, v14, s[26:27] offset:4
	s_add_u32 s26, s26, 0x2c00
	s_addc_u32 s27, s27, 0
	global_store_dword v237, v6, s[26:27]
	global_store_dword v237, v10, s[26:27] offset:4
	s_add_u32 s26, s26, 0x2c00
	s_addc_u32 s27, s27, 0
	global_store_dword v237, v3, s[26:27]
	global_store_dword v237, v15, s[26:27] offset:4
	s_add_u32 s26, s26, 0x2c00
	s_addc_u32 s27, s27, 0
	global_store_dword v237, v7, s[26:27]
	global_store_dword v237, v11, s[26:27] offset:4
	s_add_u32 s26, s26, 0x2c00
	s_addc_u32 s27, s27, 0
	s_or_b64 exec, exec, s[16:17]
; #define PG8_LAS __attribute__((address_space(3)))
;     __device__ __forceinline__ void operator()(const f32x4 (&acc)[2][2][4][2], const Unit& u, int wr, int wc, int fr, int fq) const {
;     ...
;                 float o[2][4];
; #pragma unroll
;                 for (int n = 0; n < 2; ++n) {
;                     const f32x4 Xa = acc[ai][0][m][n], Xb = acc[ai][1][m][n];
;                     float da2, da3, db2, db3;
;                     if (m > 0) { const bool t = (fq == 3); da2 = t ? acc[ai][0][m > 0 ? m - 1 : 0][n][2] : Xa[2]; da3 = t ? acc[ai][0][m > 0 ? m - 1 : 0][n][3] : Xa[3];
;                                  db2 = t ? acc[ai][1][m > 0 ? m - 1 : 0][n][2] : Xb[2]; db3 = t ? acc[ai][1][m > 0 ? m - 1 : 0][n][3] : Xb[3]; }
;                     else { da2 = Xa[2]; da3 = Xa[3]; db2 = Xb[2]; db3 = Xb[3]; }
;                     float Ha2 = __builtin_bit_cast(float, __builtin_amdgcn_ds_bpermute(src, __builtin_bit_cast(int, da2)));
;                     float Ha3 = __builtin_bit_cast(float, __builtin_amdgcn_ds_bpermute(src, __builtin_bit_cast(int, da3)));
;                     float Hb2 = __builtin_bit_cast(float, __builtin_amdgcn_ds_bpermute(src, __builtin_bit_cast(int, db2)));
;                     float Hb3 = __builtin_bit_cast(float, __builtin_amdgcn_ds_bpermute(src, __builtin_bit_cast(int, db3)));
;                     if (m == 0) {
;                         float h2a = 0.f, h3a = 0.f, h2b = 0.f, h3b = 0.f;
;                         if (blk > 0) { const PG8_LAS float* hp = halo + ((((blk - 1) * 4 + wc) * 2 + 0) * 2 + n) * 32 + fr; h2a = hp[0]; h3a = hp[16]; h2b = hp[64]; h3b = hp[80]; }
;                         if (fq == 0) { Ha2 = h2a; Ha3 = h3a; Hb2 = h2b; Hb3 = h3b; }
;                     }
;                     const f32x2_t W0 = {wa[n][0], wb[n][0]}, W1 = {wa[n][1], wb[n][1]}, W2 = {wa[n][2], wb[n][2]}, B2 = {ba[n], bb[n]};
;                     const f32x2_t H2 = {Ha2, Hb2}, H3 = {Ha3, Hb3}, X0 = {Xa[0], Xb[0]}, X1 = {Xa[1], Xb[1]}, X2 = {Xa[2], Xb[2]}, X3 = {Xa[3], Xb[3]};
;                     const f32x2_t y0 = B2 + W0 * H2 + W1 * H3 + W2 * X0, y1 = B2 + W0 * H3 + W1 * X0 + W2 * X1, y2 = B2 + W0 * X0 + W1 * X1 + W2 * X2, y3 = B2 + W0 * X1 + W1 * X2 + W2 * X3;
;                     const float ya0 = y0[0], yb0 = y0[1], ya1 = y1[0], yb1 = y1[1], ya2 = y2[0], yb2 = y2[1], ya3 = y3[0], yb3 = y3[1];
.Lp8_side_done:
	s_mul_i32 s76, s74, 0x160000
	s_add_u32 s76, s40, s76
	s_addc_u32 s77, s41, 0
	s_waitcnt lgkmcnt(13)
	ds_bpermute_b32 v204, v158, v110
	s_waitcnt lgkmcnt(13)
	ds_bpermute_b32 v205, v158, v111
	s_waitcnt lgkmcnt(13)
	ds_bpermute_b32 v206, v158, v106
	s_waitcnt lgkmcnt(13)
	ds_bpermute_b32 v207, v158, v107
	s_waitcnt lgkmcnt(13)
	ds_bpermute_b32 v208, v158, v102
	s_waitcnt lgkmcnt(13)
	ds_bpermute_b32 v209, v158, v103
	s_waitcnt lgkmcnt(13)
	ds_bpermute_b32 v210, v158, v98
	s_waitcnt lgkmcnt(13)
	ds_bpermute_b32 v211, v158, v99
	s_waitcnt lgkmcnt(12)
	v_cndmask_b32_e64 v140, v196, v228, s[8:9]
	v_cndmask_b32_e64 v141, v197, v229, s[8:9]
	v_cndmask_b32_e64 v142, v198, v230, s[8:9]
	v_cndmask_b32_e64 v143, v199, v231, s[8:9]
	v_pk_fma_f32 v[164:165], v[238:239], v[140:141], v[250:251] op_sel_hi:[0,1,0]
	v_pk_fma_f32 v[168:169], v[244:245], v[142:143], v[252:253] op_sel_hi:[0,1,0]
	v_pk_fma_f32 v[166:167], v[238:239], v[124:125], v[250:251] op_sel_hi:[0,1,0]
	v_pk_fma_f32 v[170:171], v[244:245], v[120:121], v[252:253] op_sel_hi:[0,1,0]
	v_pk_fma_f32 v[164:165], v[242:243], v[124:125], v[164:165] op_sel_hi:[0,1,1]
	v_pk_fma_f32 v[168:169], v[248:249], v[120:121], v[168:169] op_sel_hi:[0,1,1]
	v_pk_fma_f32 v[166:167], v[242:243], v[126:127], v[166:167] op_sel_hi:[0,1,1]
	v_pk_fma_f32 v[170:171], v[248:249], v[122:123], v[170:171] op_sel_hi:[0,1,1]
	v_fmac_f32_e32 v164, v240, v141
	v_fmac_f32_e32 v168, v246, v143
	v_fmac_f32_e32 v165, v240, v124
	v_fmac_f32_e32 v169, v246, v120
	v_fmac_f32_e32 v166, v240, v125
	v_fmac_f32_e32 v170, v246, v121
	v_fmac_f32_e32 v167, v240, v126
	v_fmac_f32_e32 v171, v246, v122
	v_exp_f32_e32 v144, v164
	v_exp_f32_e32 v145, v165
	v_exp_f32_e32 v146, v166
	v_exp_f32_e32 v147, v167
	v_pk_mul_f32 v[164:165], v[164:165], v[168:169]
	v_pk_mul_f32 v[166:167], v[166:167], v[170:171]
	v_pk_add_f32 v[144:145], v[144:145], v[162:163]
	v_pk_add_f32 v[146:147], v[146:147], v[162:163]
	v_rcp_f32_e32 v144, v144
	v_rcp_f32_e32 v145, v145
	v_rcp_f32_e32 v146, v146
	v_rcp_f32_e32 v147, v147
	s_waitcnt lgkmcnt(8)
	v_cndmask_b32_e64 v140, v200, v232, s[8:9]
	v_cndmask_b32_e64 v141, v201, v233, s[8:9]
	v_cndmask_b32_e64 v142, v202, v234, s[8:9]
	v_cndmask_b32_e64 v143, v203, v235, s[8:9]
	v_pk_fma_f32 v[182:183], v[238:239], v[140:141], v[250:251] op_sel:[1,0,1] op_sel_hi:[1,1,1]
	v_pk_fma_f32 v[186:187], v[244:245], v[142:143], v[252:253] op_sel:[1,0,1] op_sel_hi:[1,1,1]
	v_pk_fma_f32 v[184:185], v[238:239], v[116:117], v[250:251] op_sel:[1,0,1] op_sel_hi:[1,1,1]
	v_pk_fma_f32 v[188:189], v[244:245], v[112:113], v[252:253] op_sel:[1,0,1] op_sel_hi:[1,1,1]
	v_pk_fma_f32 v[182:183], v[242:243], v[116:117], v[182:183] op_sel:[1,0,0] op_sel_hi:[1,1,1]
	v_pk_fma_f32 v[186:187], v[248:249], v[112:113], v[186:187] op_sel:[1,0,0] op_sel_hi:[1,1,1]
	v_pk_fma_f32 v[184:185], v[242:243], v[118:119], v[184:185] op_sel:[1,0,0] op_sel_hi:[1,1,1]
	v_pk_fma_f32 v[188:189], v[248:249], v[114:115], v[188:189] op_sel:[1,0,0] op_sel_hi:[1,1,1]
	v_fmac_f32_e32 v182, v241, v141
	v_fmac_f32_e32 v186, v247, v143
	v_fmac_f32_e32 v183, v241, v116
	v_fmac_f32_e32 v187, v247, v112
	v_fmac_f32_e32 v184, v241, v117
	v_fmac_f32_e32 v188, v247, v113
	v_fmac_f32_e32 v185, v241, v118
	v_fmac_f32_e32 v189, v247, v114
	v_exp_f32_e32 v148, v182
	v_exp_f32_e32 v149, v183
	v_exp_f32_e32 v150, v184
	v_exp_f32_e32 v151, v185
	v_pk_mul_f32 v[182:183], v[182:183], v[186:187]
	v_pk_mul_f32 v[184:185], v[184:185], v[188:189]
	v_pk_add_f32 v[148:149], v[148:149], v[162:163]
	v_pk_add_f32 v[150:151], v[150:151], v[162:163]
	v_rcp_f32_e32 v148, v148
	v_rcp_f32_e32 v149, v149
	v_rcp_f32_e32 v150, v150
	v_rcp_f32_e32 v151, v151
	v_pk_mul_f32 v[164:165], v[164:165], v[144:145]
	v_pk_mul_f32 v[166:167], v[166:167], v[146:147]
	v_pk_mul_f32 v[182:183], v[182:183], v[148:149]
	v_pk_mul_f32 v[184:185], v[184:185], v[150:151]
	v_cvt_pk_bf16_f32 v152, v164, v182
	v_cvt_pk_bf16_f32 v153, v165, v183
	v_cvt_pk_bf16_f32 v154, v166, v184
	v_cvt_pk_bf16_f32 v155, v167, v185
	global_store_dword v157, v152, s[76:77]
	s_add_u32 s76, s76, 0x1600
	s_addc_u32 s77, s77, 0
	global_store_dword v157, v153, s[76:77]
	s_add_u32 s76, s76, 0x1600
	s_addc_u32 s77, s77, 0
	global_store_dword v157, v154, s[76:77]
	s_add_u32 s76, s76, 0x1600
	s_addc_u32 s77, s77, 0
	global_store_dword v157, v155, s[76:77]
	s_add_u32 s76, s76, 0x11e00
	s_addc_u32 s77, s77, 0
	ds_bpermute_b32 v212, v158, v94
	ds_bpermute_b32 v213, v158, v95
	ds_bpermute_b32 v214, v158, v90
	ds_bpermute_b32 v215, v158, v91
	ds_bpermute_b32 v216, v158, v86
	ds_bpermute_b32 v217, v158, v87
	s_waitcnt lgkmcnt(13)
	ds_bpermute_b32 v218, v158, v82
	s_waitcnt lgkmcnt(13)
	ds_bpermute_b32 v219, v158, v83
	s_waitcnt lgkmcnt(13)
	ds_read_b32 v228, v159 offset:2048
	s_waitcnt lgkmcnt(13)
	ds_read_b32 v229, v159 offset:2112
	s_waitcnt lgkmcnt(13)
	ds_read_b32 v230, v159 offset:2304
	s_waitcnt lgkmcnt(13)
	ds_read_b32 v231, v159 offset:2368
	s_waitcnt lgkmcnt(13)
	ds_read_b32 v232, v159 offset:2176
	s_waitcnt lgkmcnt(13)
	ds_read_b32 v233, v159 offset:2240
	s_waitcnt lgkmcnt(13)
	ds_read_b32 v234, v159 offset:2432
	s_waitcnt lgkmcnt(13)
; #define PG8_LAS __attribute__((address_space(3)))
;     __device__ __forceinline__ void operator()(const f32x4 (&acc)[2][2][4][2], const Unit& u, int wr, int wc, int fr, int fq) const {
;     ...
;                 float o[2][4];
; #pragma unroll
;                 for (int n = 0; n < 2; ++n) {
;                     const f32x4 Xa = acc[ai][0][m][n], Xb = acc[ai][1][m][n];
;                     float da2, da3, db2, db3;
;                     if (m > 0) { const bool t = (fq == 3); da2 = t ? acc[ai][0][m > 0 ? m - 1 : 0][n][2] : Xa[2]; da3 = t ? acc[ai][0][m > 0 ? m - 1 : 0][n][3] : Xa[3];
;                                  db2 = t ? acc[ai][1][m > 0 ? m - 1 : 0][n][2] : Xb[2]; db3 = t ? acc[ai][1][m > 0 ? m - 1 : 0][n][3] : Xb[3]; }
;                     else { da2 = Xa[2]; da3 = Xa[3]; db2 = Xb[2]; db3 = Xb[3]; }
;                     float Ha2 = __builtin_bit_cast(float, __builtin_amdgcn_ds_bpermute(src, __builtin_bit_cast(int, da2)));
;                     float Ha3 = __builtin_bit_cast(float, __builtin_amdgcn_ds_bpermute(src, __builtin_bit_cast(int, da3)));
;                     float Hb2 = __builtin_bit_cast(float, __builtin_amdgcn_ds_bpermute(src, __builtin_bit_cast(int, db2)));
;                     float Hb3 = __builtin_bit_cast(float, __builtin_amdgcn_ds_bpermute(src, __builtin_bit_cast(int, db3)));
;                     if (m == 0) {
;                         float h2a = 0.f, h3a = 0.f, h2b = 0.f, h3b = 0.f;
;                         if (blk > 0) { const PG8_LAS float* hp = halo + ((((blk - 1) * 4 + wc) * 2 + 0) * 2 + n) * 32 + fr; h2a = hp[0]; h3a = hp[16]; h2b = hp[64]; h3b = hp[80]; }
;                         if (fq == 0) { Ha2 = h2a; Ha3 = h3a; Hb2 = h2b; Hb3 = h3b; }
;                     }
;                     const f32x2_t W0 = {wa[n][0], wb[n][0]}, W1 = {wa[n][1], wb[n][1]}, W2 = {wa[n][2], wb[n][2]}, B2 = {ba[n], bb[n]};
;                     const f32x2_t H2 = {Ha2, Hb2}, H3 = {Ha3, Hb3}, X0 = {Xa[0], Xb[0]}, X1 = {Xa[1], Xb[1]}, X2 = {Xa[2], Xb[2]}, X3 = {Xa[3], Xb[3]};
;                     const f32x2_t y0 = B2 + W0 * H2 + W1 * H3 + W2 * X0, y1 = B2 + W0 * H3 + W1 * X0 + W2 * X1, y2 = B2 + W0 * X0 + W1 * X1 + W2 * X2, y3 = B2 + W0 * X1 + W1 * X2 + W2 * X3;
;                     const float ya0 = y0[0], yb0 = y0[1], ya1 = y1[0], yb1 = y1[1], ya2 = y2[0], yb2 = y2[1], ya3 = y3[0], yb3 = y3[1];
	ds_read_b32 v235, v159 offset:2496
	v_cndmask_b32_e64 v140, v204, v196, s[8:9]
	v_cndmask_b32_e64 v141, v205, v197, s[8:9]
	v_cndmask_b32_e64 v142, v206, v198, s[8:9]
	v_cndmask_b32_e64 v143, v207, v199, s[8:9]
	v_pk_fma_f32 v[164:165], v[238:239], v[140:141], v[250:251] op_sel_hi:[0,1,0]
	v_pk_fma_f32 v[168:169], v[244:245], v[142:143], v[252:253] op_sel_hi:[0,1,0]
	v_pk_fma_f32 v[166:167], v[238:239], v[108:109], v[250:251] op_sel_hi:[0,1,0]
	v_pk_fma_f32 v[170:171], v[244:245], v[104:105], v[252:253] op_sel_hi:[0,1,0]
	v_pk_fma_f32 v[164:165], v[242:243], v[108:109], v[164:165] op_sel_hi:[0,1,1]
	v_pk_fma_f32 v[168:169], v[248:249], v[104:105], v[168:169] op_sel_hi:[0,1,1]
	v_pk_fma_f32 v[166:167], v[242:243], v[110:111], v[166:167] op_sel_hi:[0,1,1]
	v_pk_fma_f32 v[170:171], v[248:249], v[106:107], v[170:171] op_sel_hi:[0,1,1]
	v_fmac_f32_e32 v164, v240, v141
	v_fmac_f32_e32 v168, v246, v143
	v_fmac_f32_e32 v165, v240, v108
	v_fmac_f32_e32 v169, v246, v104
	v_fmac_f32_e32 v166, v240, v109
	v_fmac_f32_e32 v170, v246, v105
	v_fmac_f32_e32 v167, v240, v110
	v_fmac_f32_e32 v171, v246, v106
	v_exp_f32_e32 v144, v164
	v_exp_f32_e32 v145, v165
	v_exp_f32_e32 v146, v166
	v_exp_f32_e32 v147, v167
	v_pk_mul_f32 v[164:165], v[164:165], v[168:169]
	v_pk_mul_f32 v[166:167], v[166:167], v[170:171]
	v_pk_add_f32 v[144:145], v[144:145], v[162:163]
	v_pk_add_f32 v[146:147], v[146:147], v[162:163]
	v_rcp_f32_e32 v144, v144
	v_rcp_f32_e32 v145, v145
	v_rcp_f32_e32 v146, v146
	v_rcp_f32_e32 v147, v147
	v_cndmask_b32_e64 v140, v208, v200, s[8:9]
	v_cndmask_b32_e64 v141, v209, v201, s[8:9]
	v_cndmask_b32_e64 v142, v210, v202, s[8:9]
	v_cndmask_b32_e64 v143, v211, v203, s[8:9]
	v_pk_fma_f32 v[182:183], v[238:239], v[140:141], v[250:251] op_sel:[1,0,1] op_sel_hi:[1,1,1]
	v_pk_fma_f32 v[186:187], v[244:245], v[142:143], v[252:253] op_sel:[1,0,1] op_sel_hi:[1,1,1]
	v_pk_fma_f32 v[184:185], v[238:239], v[100:101], v[250:251] op_sel:[1,0,1] op_sel_hi:[1,1,1]
	v_pk_fma_f32 v[188:189], v[244:245], v[96:97], v[252:253] op_sel:[1,0,1] op_sel_hi:[1,1,1]
	v_pk_fma_f32 v[182:183], v[242:243], v[100:101], v[182:183] op_sel:[1,0,0] op_sel_hi:[1,1,1]
	v_pk_fma_f32 v[186:187], v[248:249], v[96:97], v[186:187] op_sel:[1,0,0] op_sel_hi:[1,1,1]
	v_pk_fma_f32 v[184:185], v[242:243], v[102:103], v[184:185] op_sel:[1,0,0] op_sel_hi:[1,1,1]
	v_pk_fma_f32 v[188:189], v[248:249], v[98:99], v[188:189] op_sel:[1,0,0] op_sel_hi:[1,1,1]
	v_fmac_f32_e32 v182, v241, v141
	v_fmac_f32_e32 v186, v247, v143
	v_fmac_f32_e32 v183, v241, v100
	v_fmac_f32_e32 v187, v247, v96
	v_fmac_f32_e32 v184, v241, v101
	v_fmac_f32_e32 v188, v247, v97
	v_fmac_f32_e32 v185, v241, v102
	v_fmac_f32_e32 v189, v247, v98
	v_exp_f32_e32 v148, v182
	v_exp_f32_e32 v149, v183
	v_exp_f32_e32 v150, v184
	v_exp_f32_e32 v151, v185
	v_pk_mul_f32 v[182:183], v[182:183], v[186:187]
	v_pk_mul_f32 v[184:185], v[184:185], v[188:189]
	v_pk_add_f32 v[148:149], v[148:149], v[162:163]
	v_pk_add_f32 v[150:151], v[150:151], v[162:163]
	v_rcp_f32_e32 v148, v148
	v_rcp_f32_e32 v149, v149
	v_rcp_f32_e32 v150, v150
	v_rcp_f32_e32 v151, v151
	v_pk_mul_f32 v[164:165], v[164:165], v[144:145]
	v_pk_mul_f32 v[166:167], v[166:167], v[146:147]
	v_pk_mul_f32 v[182:183], v[182:183], v[148:149]
	v_pk_mul_f32 v[184:185], v[184:185], v[150:151]
	v_cvt_pk_bf16_f32 v152, v164, v182
	v_cvt_pk_bf16_f32 v153, v165, v183
	v_cvt_pk_bf16_f32 v154, v166, v184
	v_cvt_pk_bf16_f32 v155, v167, v185
	global_store_dword v157, v152, s[76:77]
	s_add_u32 s76, s76, 0x1600
	s_addc_u32 s77, s77, 0
	global_store_dword v157, v153, s[76:77]
	s_add_u32 s76, s76, 0x1600
	s_addc_u32 s77, s77, 0
	global_store_dword v157, v154, s[76:77]
	s_add_u32 s76, s76, 0x1600
	s_addc_u32 s77, s77, 0
	global_store_dword v157, v155, s[76:77]
	s_add_u32 s76, s76, 0x11e00
	s_addc_u32 s77, s77, 0
	s_waitcnt lgkmcnt(13)
	ds_bpermute_b32 v220, v158, v70
	s_waitcnt lgkmcnt(13)
	ds_bpermute_b32 v221, v158, v71
	s_waitcnt lgkmcnt(13)
	ds_bpermute_b32 v222, v158, v66
	s_waitcnt lgkmcnt(13)
	ds_bpermute_b32 v223, v158, v67
	s_waitcnt lgkmcnt(13)
	ds_bpermute_b32 v224, v158, v78
	s_waitcnt lgkmcnt(13)
	ds_bpermute_b32 v225, v158, v79
	s_waitcnt lgkmcnt(13)
	ds_bpermute_b32 v226, v158, v74
	s_waitcnt lgkmcnt(13)
	ds_bpermute_b32 v227, v158, v75
	v_cndmask_b32_e64 v140, v212, v204, s[8:9]
	v_cndmask_b32_e64 v141, v213, v205, s[8:9]
	v_cndmask_b32_e64 v142, v214, v206, s[8:9]
	v_cndmask_b32_e64 v143, v215, v207, s[8:9]
	v_pk_fma_f32 v[164:165], v[238:239], v[140:141], v[250:251] op_sel_hi:[0,1,0]
	v_pk_fma_f32 v[168:169], v[244:245], v[142:143], v[252:253] op_sel_hi:[0,1,0]
	v_pk_fma_f32 v[166:167], v[238:239], v[92:93], v[250:251] op_sel_hi:[0,1,0]
	v_pk_fma_f32 v[170:171], v[244:245], v[88:89], v[252:253] op_sel_hi:[0,1,0]
	v_pk_fma_f32 v[164:165], v[242:243], v[92:93], v[164:165] op_sel_hi:[0,1,1]
	v_pk_fma_f32 v[168:169], v[248:249], v[88:89], v[168:169] op_sel_hi:[0,1,1]
	v_pk_fma_f32 v[166:167], v[242:243], v[94:95], v[166:167] op_sel_hi:[0,1,1]
	v_pk_fma_f32 v[170:171], v[248:249], v[90:91], v[170:171] op_sel_hi:[0,1,1]
	v_fmac_f32_e32 v164, v240, v141
	v_fmac_f32_e32 v168, v246, v143
	v_fmac_f32_e32 v165, v240, v92
	v_fmac_f32_e32 v169, v246, v88
	v_fmac_f32_e32 v166, v240, v93
	v_fmac_f32_e32 v170, v246, v89
	v_fmac_f32_e32 v167, v240, v94
	v_fmac_f32_e32 v171, v246, v90
	v_exp_f32_e32 v144, v164
	v_exp_f32_e32 v145, v165
	v_exp_f32_e32 v146, v166
	v_exp_f32_e32 v147, v167
	v_pk_mul_f32 v[164:165], v[164:165], v[168:169]
	v_pk_mul_f32 v[166:167], v[166:167], v[170:171]
	v_pk_add_f32 v[144:145], v[144:145], v[162:163]
	v_pk_add_f32 v[146:147], v[146:147], v[162:163]
	v_rcp_f32_e32 v144, v144
; #define PG8_LAS __attribute__((address_space(3)))
;     __device__ __forceinline__ void operator()(const f32x4 (&acc)[2][2][4][2], const Unit& u, int wr, int wc, int fr, int fq) const {
;     ...
;                 float o[2][4];
; #pragma unroll
;                 for (int n = 0; n < 2; ++n) {
;                     const f32x4 Xa = acc[ai][0][m][n], Xb = acc[ai][1][m][n];
;                     float da2, da3, db2, db3;
;                     if (m > 0) { const bool t = (fq == 3); da2 = t ? acc[ai][0][m > 0 ? m - 1 : 0][n][2] : Xa[2]; da3 = t ? acc[ai][0][m > 0 ? m - 1 : 0][n][3] : Xa[3];
;                                  db2 = t ? acc[ai][1][m > 0 ? m - 1 : 0][n][2] : Xb[2]; db3 = t ? acc[ai][1][m > 0 ? m - 1 : 0][n][3] : Xb[3]; }
;                     else { da2 = Xa[2]; da3 = Xa[3]; db2 = Xb[2]; db3 = Xb[3]; }
;                     float Ha2 = __builtin_bit_cast(float, __builtin_amdgcn_ds_bpermute(src, __builtin_bit_cast(int, da2)));
;                     float Ha3 = __builtin_bit_cast(float, __builtin_amdgcn_ds_bpermute(src, __builtin_bit_cast(int, da3)));
;                     float Hb2 = __builtin_bit_cast(float, __builtin_amdgcn_ds_bpermute(src, __builtin_bit_cast(int, db2)));
;                     float Hb3 = __builtin_bit_cast(float, __builtin_amdgcn_ds_bpermute(src, __builtin_bit_cast(int, db3)));
;                     if (m == 0) {
;                         float h2a = 0.f, h3a = 0.f, h2b = 0.f, h3b = 0.f;
;                         if (blk > 0) { const PG8_LAS float* hp = halo + ((((blk - 1) * 4 + wc) * 2 + 0) * 2 + n) * 32 + fr; h2a = hp[0]; h3a = hp[16]; h2b = hp[64]; h3b = hp[80]; }
;                         if (fq == 0) { Ha2 = h2a; Ha3 = h3a; Hb2 = h2b; Hb3 = h3b; }
;                     }
;                     const f32x2_t W0 = {wa[n][0], wb[n][0]}, W1 = {wa[n][1], wb[n][1]}, W2 = {wa[n][2], wb[n][2]}, B2 = {ba[n], bb[n]};
;                     const f32x2_t H2 = {Ha2, Hb2}, H3 = {Ha3, Hb3}, X0 = {Xa[0], Xb[0]}, X1 = {Xa[1], Xb[1]}, X2 = {Xa[2], Xb[2]}, X3 = {Xa[3], Xb[3]};
;                     const f32x2_t y0 = B2 + W0 * H2 + W1 * H3 + W2 * X0, y1 = B2 + W0 * H3 + W1 * X0 + W2 * X1, y2 = B2 + W0 * X0 + W1 * X1 + W2 * X2, y3 = B2 + W0 * X1 + W1 * X2 + W2 * X3;
;                     const float ya0 = y0[0], yb0 = y0[1], ya1 = y1[0], yb1 = y1[1], ya2 = y2[0], yb2 = y2[1], ya3 = y3[0], yb3 = y3[1];
	v_rcp_f32_e32 v145, v145
	v_rcp_f32_e32 v146, v146
	v_rcp_f32_e32 v147, v147
	v_cndmask_b32_e64 v140, v216, v208, s[8:9]
	v_cndmask_b32_e64 v141, v217, v209, s[8:9]
	v_cndmask_b32_e64 v142, v218, v210, s[8:9]
	v_cndmask_b32_e64 v143, v219, v211, s[8:9]
	v_pk_fma_f32 v[182:183], v[238:239], v[140:141], v[250:251] op_sel:[1,0,1] op_sel_hi:[1,1,1]
	v_pk_fma_f32 v[186:187], v[244:245], v[142:143], v[252:253] op_sel:[1,0,1] op_sel_hi:[1,1,1]
	v_pk_fma_f32 v[184:185], v[238:239], v[84:85], v[250:251] op_sel:[1,0,1] op_sel_hi:[1,1,1]
	v_pk_fma_f32 v[188:189], v[244:245], v[80:81], v[252:253] op_sel:[1,0,1] op_sel_hi:[1,1,1]
	v_pk_fma_f32 v[182:183], v[242:243], v[84:85], v[182:183] op_sel:[1,0,0] op_sel_hi:[1,1,1]
	v_pk_fma_f32 v[186:187], v[248:249], v[80:81], v[186:187] op_sel:[1,0,0] op_sel_hi:[1,1,1]
	v_pk_fma_f32 v[184:185], v[242:243], v[86:87], v[184:185] op_sel:[1,0,0] op_sel_hi:[1,1,1]
	v_pk_fma_f32 v[188:189], v[248:249], v[82:83], v[188:189] op_sel:[1,0,0] op_sel_hi:[1,1,1]
	v_fmac_f32_e32 v182, v241, v141
	v_fmac_f32_e32 v186, v247, v143
	v_fmac_f32_e32 v183, v241, v84
	v_fmac_f32_e32 v187, v247, v80
	v_fmac_f32_e32 v184, v241, v85
	v_fmac_f32_e32 v188, v247, v81
	v_fmac_f32_e32 v185, v241, v86
	v_fmac_f32_e32 v189, v247, v82
	v_exp_f32_e32 v148, v182
	v_exp_f32_e32 v149, v183
	v_exp_f32_e32 v150, v184
	v_exp_f32_e32 v151, v185
	v_pk_mul_f32 v[182:183], v[182:183], v[186:187]
	v_pk_mul_f32 v[184:185], v[184:185], v[188:189]
	v_pk_add_f32 v[148:149], v[148:149], v[162:163]
	v_pk_add_f32 v[150:151], v[150:151], v[162:163]
	v_rcp_f32_e32 v148, v148
	v_rcp_f32_e32 v149, v149
	v_rcp_f32_e32 v150, v150
	v_rcp_f32_e32 v151, v151
	v_pk_mul_f32 v[164:165], v[164:165], v[144:145]
	v_pk_mul_f32 v[166:167], v[166:167], v[146:147]
	v_pk_mul_f32 v[182:183], v[182:183], v[148:149]
	v_pk_mul_f32 v[184:185], v[184:185], v[150:151]
	v_cvt_pk_bf16_f32 v152, v164, v182
	v_cvt_pk_bf16_f32 v153, v165, v183
	v_cvt_pk_bf16_f32 v154, v166, v184
	v_cvt_pk_bf16_f32 v155, v167, v185
	global_store_dword v157, v152, s[76:77]
	s_add_u32 s76, s76, 0x1600
	s_addc_u32 s77, s77, 0
	global_store_dword v157, v153, s[76:77]
	s_add_u32 s76, s76, 0x1600
	s_addc_u32 s77, s77, 0
	global_store_dword v157, v154, s[76:77]
	s_add_u32 s76, s76, 0x1600
	s_addc_u32 s77, s77, 0
	global_store_dword v157, v155, s[76:77]
	s_add_u32 s76, s76, 0x11e00
	s_addc_u32 s77, s77, 0
	s_waitcnt lgkmcnt(13)
	ds_bpermute_b32 v196, v158, v62
	s_waitcnt lgkmcnt(13)
	ds_bpermute_b32 v197, v158, v63
	s_waitcnt lgkmcnt(13)
	ds_bpermute_b32 v198, v158, v58
	s_waitcnt lgkmcnt(13)
	ds_bpermute_b32 v199, v158, v59
	s_waitcnt lgkmcnt(13)
	ds_bpermute_b32 v200, v158, v54
	s_waitcnt lgkmcnt(13)
	ds_bpermute_b32 v201, v158, v55
	s_waitcnt lgkmcnt(13)
	ds_bpermute_b32 v202, v158, v50
	s_waitcnt lgkmcnt(13)
	ds_bpermute_b32 v203, v158, v51
	s_waitcnt lgkmcnt(12)
	v_cndmask_b32_e64 v140, v220, v212, s[8:9]
	v_cndmask_b32_e64 v141, v221, v213, s[8:9]
	v_cndmask_b32_e64 v142, v222, v214, s[8:9]
	v_cndmask_b32_e64 v143, v223, v215, s[8:9]
	v_pk_fma_f32 v[164:165], v[238:239], v[140:141], v[250:251] op_sel_hi:[0,1,0]
	v_pk_fma_f32 v[168:169], v[244:245], v[142:143], v[252:253] op_sel_hi:[0,1,0]
	v_pk_fma_f32 v[166:167], v[238:239], v[68:69], v[250:251] op_sel_hi:[0,1,0]
	v_pk_fma_f32 v[170:171], v[244:245], v[64:65], v[252:253] op_sel_hi:[0,1,0]
	v_pk_fma_f32 v[164:165], v[242:243], v[68:69], v[164:165] op_sel_hi:[0,1,1]
	v_pk_fma_f32 v[168:169], v[248:249], v[64:65], v[168:169] op_sel_hi:[0,1,1]
	v_pk_fma_f32 v[166:167], v[242:243], v[70:71], v[166:167] op_sel_hi:[0,1,1]
	v_pk_fma_f32 v[170:171], v[248:249], v[66:67], v[170:171] op_sel_hi:[0,1,1]
	v_fmac_f32_e32 v164, v240, v141
	v_fmac_f32_e32 v168, v246, v143
	v_fmac_f32_e32 v165, v240, v68
	v_fmac_f32_e32 v169, v246, v64
	v_fmac_f32_e32 v166, v240, v69
	v_fmac_f32_e32 v170, v246, v65
	v_fmac_f32_e32 v167, v240, v70
	v_fmac_f32_e32 v171, v246, v66
	v_exp_f32_e32 v144, v164
	v_exp_f32_e32 v145, v165
	v_exp_f32_e32 v146, v166
	v_exp_f32_e32 v147, v167
	v_pk_mul_f32 v[164:165], v[164:165], v[168:169]
	v_pk_mul_f32 v[166:167], v[166:167], v[170:171]
	v_pk_add_f32 v[144:145], v[144:145], v[162:163]
	v_pk_add_f32 v[146:147], v[146:147], v[162:163]
	v_rcp_f32_e32 v144, v144
	v_rcp_f32_e32 v145, v145
	v_rcp_f32_e32 v146, v146
	v_rcp_f32_e32 v147, v147
	s_waitcnt lgkmcnt(8)
	v_cndmask_b32_e64 v140, v224, v216, s[8:9]
	v_cndmask_b32_e64 v141, v225, v217, s[8:9]
	v_cndmask_b32_e64 v142, v226, v218, s[8:9]
	v_cndmask_b32_e64 v143, v227, v219, s[8:9]
	v_pk_fma_f32 v[182:183], v[238:239], v[140:141], v[250:251] op_sel:[1,0,1] op_sel_hi:[1,1,1]
	v_pk_fma_f32 v[186:187], v[244:245], v[142:143], v[252:253] op_sel:[1,0,1] op_sel_hi:[1,1,1]
	v_pk_fma_f32 v[184:185], v[238:239], v[76:77], v[250:251] op_sel:[1,0,1] op_sel_hi:[1,1,1]
	v_pk_fma_f32 v[188:189], v[244:245], v[72:73], v[252:253] op_sel:[1,0,1] op_sel_hi:[1,1,1]
	v_pk_fma_f32 v[182:183], v[242:243], v[76:77], v[182:183] op_sel:[1,0,0] op_sel_hi:[1,1,1]
	v_pk_fma_f32 v[186:187], v[248:249], v[72:73], v[186:187] op_sel:[1,0,0] op_sel_hi:[1,1,1]
	v_pk_fma_f32 v[184:185], v[242:243], v[78:79], v[184:185] op_sel:[1,0,0] op_sel_hi:[1,1,1]
	v_pk_fma_f32 v[188:189], v[248:249], v[74:75], v[188:189] op_sel:[1,0,0] op_sel_hi:[1,1,1]
	v_fmac_f32_e32 v182, v241, v141
	v_fmac_f32_e32 v186, v247, v143
	v_fmac_f32_e32 v183, v241, v76
	v_fmac_f32_e32 v187, v247, v72
	v_fmac_f32_e32 v184, v241, v77
	v_fmac_f32_e32 v188, v247, v73
	v_fmac_f32_e32 v185, v241, v78
	v_fmac_f32_e32 v189, v247, v74
	v_exp_f32_e32 v148, v182
	v_exp_f32_e32 v149, v183
	v_exp_f32_e32 v150, v184
	v_exp_f32_e32 v151, v185
	v_pk_mul_f32 v[182:183], v[182:183], v[186:187]
	v_pk_mul_f32 v[184:185], v[184:185], v[188:189]
	v_pk_add_f32 v[148:149], v[148:149], v[162:163]
	v_pk_add_f32 v[150:151], v[150:151], v[162:163]
	v_rcp_f32_e32 v148, v148
	v_rcp_f32_e32 v149, v149
	v_rcp_f32_e32 v150, v150
	v_rcp_f32_e32 v151, v151
	v_pk_mul_f32 v[164:165], v[164:165], v[144:145]
	v_pk_mul_f32 v[166:167], v[166:167], v[146:147]
	v_pk_mul_f32 v[182:183], v[182:183], v[148:149]
	v_pk_mul_f32 v[184:185], v[184:185], v[150:151]
	v_cvt_pk_bf16_f32 v152, v164, v182
	v_cvt_pk_bf16_f32 v153, v165, v183
	v_cvt_pk_bf16_f32 v154, v166, v184
	v_cvt_pk_bf16_f32 v155, v167, v185
	global_store_dword v157, v152, s[76:77]
	s_add_u32 s76, s76, 0x1600
	s_addc_u32 s77, s77, 0
	global_store_dword v157, v153, s[76:77]
	s_add_u32 s76, s76, 0x1600
	s_addc_u32 s77, s77, 0
	global_store_dword v157, v154, s[76:77]
	s_add_u32 s76, s76, 0x1600
	s_addc_u32 s77, s77, 0
	global_store_dword v157, v155, s[76:77]
	s_add_u32 s76, s76, 0x69e00
	s_addc_u32 s77, s77, 0
	ds_bpermute_b32 v204, v158, v46
	ds_bpermute_b32 v205, v158, v47
	ds_bpermute_b32 v206, v158, v42
	ds_bpermute_b32 v207, v158, v43
	ds_bpermute_b32 v208, v158, v38
	ds_bpermute_b32 v209, v158, v39
	s_waitcnt lgkmcnt(13)
; #define PG8_LAS __attribute__((address_space(3)))
;     __device__ __forceinline__ void operator()(const f32x4 (&acc)[2][2][4][2], const Unit& u, int wr, int wc, int fr, int fq) const {
;     ...
;                 float o[2][4];
; #pragma unroll
;                 for (int n = 0; n < 2; ++n) {
;                     const f32x4 Xa = acc[ai][0][m][n], Xb = acc[ai][1][m][n];
;                     float da2, da3, db2, db3;
;                     if (m > 0) { const bool t = (fq == 3); da2 = t ? acc[ai][0][m > 0 ? m - 1 : 0][n][2] : Xa[2]; da3 = t ? acc[ai][0][m > 0 ? m - 1 : 0][n][3] : Xa[3];
;                                  db2 = t ? acc[ai][1][m > 0 ? m - 1 : 0][n][2] : Xb[2]; db3 = t ? acc[ai][1][m > 0 ? m - 1 : 0][n][3] : Xb[3]; }
;                     else { da2 = Xa[2]; da3 = Xa[3]; db2 = Xb[2]; db3 = Xb[3]; }
;                     float Ha2 = __builtin_bit_cast(float, __builtin_amdgcn_ds_bpermute(src, __builtin_bit_cast(int, da2)));
;                     float Ha3 = __builtin_bit_cast(float, __builtin_amdgcn_ds_bpermute(src, __builtin_bit_cast(int, da3)));
;                     float Hb2 = __builtin_bit_cast(float, __builtin_amdgcn_ds_bpermute(src, __builtin_bit_cast(int, db2)));
;                     float Hb3 = __builtin_bit_cast(float, __builtin_amdgcn_ds_bpermute(src, __builtin_bit_cast(int, db3)));
;                     if (m == 0) {
;                         float h2a = 0.f, h3a = 0.f, h2b = 0.f, h3b = 0.f;
;                         if (blk > 0) { const PG8_LAS float* hp = halo + ((((blk - 1) * 4 + wc) * 2 + 0) * 2 + n) * 32 + fr; h2a = hp[0]; h3a = hp[16]; h2b = hp[64]; h3b = hp[80]; }
;                         if (fq == 0) { Ha2 = h2a; Ha3 = h3a; Hb2 = h2b; Hb3 = h3b; }
;                     }
;                     const f32x2_t W0 = {wa[n][0], wb[n][0]}, W1 = {wa[n][1], wb[n][1]}, W2 = {wa[n][2], wb[n][2]}, B2 = {ba[n], bb[n]};
;                     const f32x2_t H2 = {Ha2, Hb2}, H3 = {Ha3, Hb3}, X0 = {Xa[0], Xb[0]}, X1 = {Xa[1], Xb[1]}, X2 = {Xa[2], Xb[2]}, X3 = {Xa[3], Xb[3]};
;                     const f32x2_t y0 = B2 + W0 * H2 + W1 * H3 + W2 * X0, y1 = B2 + W0 * H3 + W1 * X0 + W2 * X1, y2 = B2 + W0 * X0 + W1 * X1 + W2 * X2, y3 = B2 + W0 * X1 + W1 * X2 + W2 * X3;
;                     const float ya0 = y0[0], yb0 = y0[1], ya1 = y1[0], yb1 = y1[1], ya2 = y2[0], yb2 = y2[1], ya3 = y3[0], yb3 = y3[1];
	ds_bpermute_b32 v210, v158, v34
	s_waitcnt lgkmcnt(13)
	ds_bpermute_b32 v211, v158, v35
	s_waitcnt lgkmcnt(12)
	v_cndmask_b32_e64 v140, v196, v228, s[8:9]
	v_cndmask_b32_e64 v141, v197, v229, s[8:9]
	v_cndmask_b32_e64 v142, v198, v230, s[8:9]
	v_cndmask_b32_e64 v143, v199, v231, s[8:9]
	v_pk_fma_f32 v[164:165], v[238:239], v[140:141], v[250:251] op_sel_hi:[0,1,0]
	v_pk_fma_f32 v[168:169], v[244:245], v[142:143], v[252:253] op_sel_hi:[0,1,0]
	v_pk_fma_f32 v[166:167], v[238:239], v[60:61], v[250:251] op_sel_hi:[0,1,0]
	v_pk_fma_f32 v[170:171], v[244:245], v[56:57], v[252:253] op_sel_hi:[0,1,0]
	v_pk_fma_f32 v[164:165], v[242:243], v[60:61], v[164:165] op_sel_hi:[0,1,1]
	v_pk_fma_f32 v[168:169], v[248:249], v[56:57], v[168:169] op_sel_hi:[0,1,1]
	v_pk_fma_f32 v[166:167], v[242:243], v[62:63], v[166:167] op_sel_hi:[0,1,1]
	v_pk_fma_f32 v[170:171], v[248:249], v[58:59], v[170:171] op_sel_hi:[0,1,1]
	v_fmac_f32_e32 v164, v240, v141
	v_fmac_f32_e32 v168, v246, v143
	v_fmac_f32_e32 v165, v240, v60
	v_fmac_f32_e32 v169, v246, v56
	v_fmac_f32_e32 v166, v240, v61
	v_fmac_f32_e32 v170, v246, v57
	v_fmac_f32_e32 v167, v240, v62
	v_fmac_f32_e32 v171, v246, v58
	v_exp_f32_e32 v144, v164
	v_exp_f32_e32 v145, v165
	v_exp_f32_e32 v146, v166
	v_exp_f32_e32 v147, v167
	v_pk_mul_f32 v[164:165], v[164:165], v[168:169]
	v_pk_mul_f32 v[166:167], v[166:167], v[170:171]
	v_pk_add_f32 v[144:145], v[144:145], v[162:163]
	v_pk_add_f32 v[146:147], v[146:147], v[162:163]
	v_rcp_f32_e32 v144, v144
	v_rcp_f32_e32 v145, v145
	v_rcp_f32_e32 v146, v146
	v_rcp_f32_e32 v147, v147
	s_waitcnt lgkmcnt(8)
	v_cndmask_b32_e64 v140, v200, v232, s[8:9]
	v_cndmask_b32_e64 v141, v201, v233, s[8:9]
	v_cndmask_b32_e64 v142, v202, v234, s[8:9]
	v_cndmask_b32_e64 v143, v203, v235, s[8:9]
	v_pk_fma_f32 v[182:183], v[238:239], v[140:141], v[250:251] op_sel:[1,0,1] op_sel_hi:[1,1,1]
	v_pk_fma_f32 v[186:187], v[244:245], v[142:143], v[252:253] op_sel:[1,0,1] op_sel_hi:[1,1,1]
	v_pk_fma_f32 v[184:185], v[238:239], v[52:53], v[250:251] op_sel:[1,0,1] op_sel_hi:[1,1,1]
	v_pk_fma_f32 v[188:189], v[244:245], v[48:49], v[252:253] op_sel:[1,0,1] op_sel_hi:[1,1,1]
	v_pk_fma_f32 v[182:183], v[242:243], v[52:53], v[182:183] op_sel:[1,0,0] op_sel_hi:[1,1,1]
	v_pk_fma_f32 v[186:187], v[248:249], v[48:49], v[186:187] op_sel:[1,0,0] op_sel_hi:[1,1,1]
	v_pk_fma_f32 v[184:185], v[242:243], v[54:55], v[184:185] op_sel:[1,0,0] op_sel_hi:[1,1,1]
	v_pk_fma_f32 v[188:189], v[248:249], v[50:51], v[188:189] op_sel:[1,0,0] op_sel_hi:[1,1,1]
	v_fmac_f32_e32 v182, v241, v141
	v_fmac_f32_e32 v186, v247, v143
	v_fmac_f32_e32 v183, v241, v52
	v_fmac_f32_e32 v187, v247, v48
	v_fmac_f32_e32 v184, v241, v53
	v_fmac_f32_e32 v188, v247, v49
	v_fmac_f32_e32 v185, v241, v54
	v_fmac_f32_e32 v189, v247, v50
	v_exp_f32_e32 v148, v182
	v_exp_f32_e32 v149, v183
	v_exp_f32_e32 v150, v184
	v_exp_f32_e32 v151, v185
	v_pk_mul_f32 v[182:183], v[182:183], v[186:187]
	v_pk_mul_f32 v[184:185], v[184:185], v[188:189]
	v_pk_add_f32 v[148:149], v[148:149], v[162:163]
	v_pk_add_f32 v[150:151], v[150:151], v[162:163]
	v_rcp_f32_e32 v148, v148
	v_rcp_f32_e32 v149, v149
	v_rcp_f32_e32 v150, v150
	v_rcp_f32_e32 v151, v151
	v_pk_mul_f32 v[164:165], v[164:165], v[144:145]
	v_pk_mul_f32 v[166:167], v[166:167], v[146:147]
	v_pk_mul_f32 v[182:183], v[182:183], v[148:149]
	v_pk_mul_f32 v[184:185], v[184:185], v[150:151]
	v_cvt_pk_bf16_f32 v152, v164, v182
	v_cvt_pk_bf16_f32 v153, v165, v183
	v_cvt_pk_bf16_f32 v154, v166, v184
	v_cvt_pk_bf16_f32 v155, v167, v185
	global_store_dword v157, v152, s[76:77]
	s_add_u32 s76, s76, 0x1600
	s_addc_u32 s77, s77, 0
	global_store_dword v157, v153, s[76:77]
	s_add_u32 s76, s76, 0x1600
	s_addc_u32 s77, s77, 0
	global_store_dword v157, v154, s[76:77]
	s_add_u32 s76, s76, 0x1600
	s_addc_u32 s77, s77, 0
	global_store_dword v157, v155, s[76:77]
	s_add_u32 s76, s76, 0x11e00
	s_addc_u32 s77, s77, 0
	ds_bpermute_b32 v212, v158, v30
	ds_bpermute_b32 v213, v158, v31
	ds_bpermute_b32 v214, v158, v26
	ds_bpermute_b32 v215, v158, v27
	ds_bpermute_b32 v216, v158, v22
	ds_bpermute_b32 v217, v158, v23
	s_waitcnt lgkmcnt(13)
	ds_bpermute_b32 v218, v158, v18
	s_waitcnt lgkmcnt(13)
	ds_bpermute_b32 v219, v158, v19
	s_waitcnt lgkmcnt(12)
	v_cndmask_b32_e64 v140, v204, v196, s[8:9]
	v_cndmask_b32_e64 v141, v205, v197, s[8:9]
	v_cndmask_b32_e64 v142, v206, v198, s[8:9]
	v_cndmask_b32_e64 v143, v207, v199, s[8:9]
	v_pk_fma_f32 v[164:165], v[238:239], v[140:141], v[250:251] op_sel_hi:[0,1,0]
	v_pk_fma_f32 v[168:169], v[244:245], v[142:143], v[252:253] op_sel_hi:[0,1,0]
	v_pk_fma_f32 v[166:167], v[238:239], v[44:45], v[250:251] op_sel_hi:[0,1,0]
	v_pk_fma_f32 v[170:171], v[244:245], v[40:41], v[252:253] op_sel_hi:[0,1,0]
	v_pk_fma_f32 v[164:165], v[242:243], v[44:45], v[164:165] op_sel_hi:[0,1,1]
	v_pk_fma_f32 v[168:169], v[248:249], v[40:41], v[168:169] op_sel_hi:[0,1,1]
	v_pk_fma_f32 v[166:167], v[242:243], v[46:47], v[166:167] op_sel_hi:[0,1,1]
	v_pk_fma_f32 v[170:171], v[248:249], v[42:43], v[170:171] op_sel_hi:[0,1,1]
	v_fmac_f32_e32 v164, v240, v141
	v_fmac_f32_e32 v168, v246, v143
	v_fmac_f32_e32 v165, v240, v44
	v_fmac_f32_e32 v169, v246, v40
	v_fmac_f32_e32 v166, v240, v45
	v_fmac_f32_e32 v170, v246, v41
	v_fmac_f32_e32 v167, v240, v46
	v_fmac_f32_e32 v171, v246, v42
	v_exp_f32_e32 v144, v164
	v_exp_f32_e32 v145, v165
	v_exp_f32_e32 v146, v166
	v_exp_f32_e32 v147, v167
	v_pk_mul_f32 v[164:165], v[164:165], v[168:169]
	v_pk_mul_f32 v[166:167], v[166:167], v[170:171]
	v_pk_add_f32 v[144:145], v[144:145], v[162:163]
	v_pk_add_f32 v[146:147], v[146:147], v[162:163]
	v_rcp_f32_e32 v144, v144
	v_rcp_f32_e32 v145, v145
	v_rcp_f32_e32 v146, v146
	v_rcp_f32_e32 v147, v147
	s_waitcnt lgkmcnt(8)
; #define PG8_LAS __attribute__((address_space(3)))
;     __device__ __forceinline__ void operator()(const f32x4 (&acc)[2][2][4][2], const Unit& u, int wr, int wc, int fr, int fq) const {
;     ...
;                 float o[2][4];
; #pragma unroll
;                 for (int n = 0; n < 2; ++n) {
;                     const f32x4 Xa = acc[ai][0][m][n], Xb = acc[ai][1][m][n];
;                     float da2, da3, db2, db3;
;                     if (m > 0) { const bool t = (fq == 3); da2 = t ? acc[ai][0][m > 0 ? m - 1 : 0][n][2] : Xa[2]; da3 = t ? acc[ai][0][m > 0 ? m - 1 : 0][n][3] : Xa[3];
;                                  db2 = t ? acc[ai][1][m > 0 ? m - 1 : 0][n][2] : Xb[2]; db3 = t ? acc[ai][1][m > 0 ? m - 1 : 0][n][3] : Xb[3]; }
;                     else { da2 = Xa[2]; da3 = Xa[3]; db2 = Xb[2]; db3 = Xb[3]; }
;                     float Ha2 = __builtin_bit_cast(float, __builtin_amdgcn_ds_bpermute(src, __builtin_bit_cast(int, da2)));
;                     float Ha3 = __builtin_bit_cast(float, __builtin_amdgcn_ds_bpermute(src, __builtin_bit_cast(int, da3)));
;                     float Hb2 = __builtin_bit_cast(float, __builtin_amdgcn_ds_bpermute(src, __builtin_bit_cast(int, db2)));
;                     float Hb3 = __builtin_bit_cast(float, __builtin_amdgcn_ds_bpermute(src, __builtin_bit_cast(int, db3)));
;                     if (m == 0) {
;                         float h2a = 0.f, h3a = 0.f, h2b = 0.f, h3b = 0.f;
;                         if (blk > 0) { const PG8_LAS float* hp = halo + ((((blk - 1) * 4 + wc) * 2 + 0) * 2 + n) * 32 + fr; h2a = hp[0]; h3a = hp[16]; h2b = hp[64]; h3b = hp[80]; }
;                         if (fq == 0) { Ha2 = h2a; Ha3 = h3a; Hb2 = h2b; Hb3 = h3b; }
;                     }
;                     const f32x2_t W0 = {wa[n][0], wb[n][0]}, W1 = {wa[n][1], wb[n][1]}, W2 = {wa[n][2], wb[n][2]}, B2 = {ba[n], bb[n]};
;                     const f32x2_t H2 = {Ha2, Hb2}, H3 = {Ha3, Hb3}, X0 = {Xa[0], Xb[0]}, X1 = {Xa[1], Xb[1]}, X2 = {Xa[2], Xb[2]}, X3 = {Xa[3], Xb[3]};
;                     const f32x2_t y0 = B2 + W0 * H2 + W1 * H3 + W2 * X0, y1 = B2 + W0 * H3 + W1 * X0 + W2 * X1, y2 = B2 + W0 * X0 + W1 * X1 + W2 * X2, y3 = B2 + W0 * X1 + W1 * X2 + W2 * X3;
;                     const float ya0 = y0[0], yb0 = y0[1], ya1 = y1[0], yb1 = y1[1], ya2 = y2[0], yb2 = y2[1], ya3 = y3[0], yb3 = y3[1];
	v_cndmask_b32_e64 v140, v208, v200, s[8:9]
	v_cndmask_b32_e64 v141, v209, v201, s[8:9]
	v_cndmask_b32_e64 v142, v210, v202, s[8:9]
	v_cndmask_b32_e64 v143, v211, v203, s[8:9]
	v_pk_fma_f32 v[182:183], v[238:239], v[140:141], v[250:251] op_sel:[1,0,1] op_sel_hi:[1,1,1]
	v_pk_fma_f32 v[186:187], v[244:245], v[142:143], v[252:253] op_sel:[1,0,1] op_sel_hi:[1,1,1]
	v_pk_fma_f32 v[184:185], v[238:239], v[36:37], v[250:251] op_sel:[1,0,1] op_sel_hi:[1,1,1]
	v_pk_fma_f32 v[188:189], v[244:245], v[32:33], v[252:253] op_sel:[1,0,1] op_sel_hi:[1,1,1]
	v_pk_fma_f32 v[182:183], v[242:243], v[36:37], v[182:183] op_sel:[1,0,0] op_sel_hi:[1,1,1]
	v_pk_fma_f32 v[186:187], v[248:249], v[32:33], v[186:187] op_sel:[1,0,0] op_sel_hi:[1,1,1]
	v_pk_fma_f32 v[184:185], v[242:243], v[38:39], v[184:185] op_sel:[1,0,0] op_sel_hi:[1,1,1]
	v_pk_fma_f32 v[188:189], v[248:249], v[34:35], v[188:189] op_sel:[1,0,0] op_sel_hi:[1,1,1]
	v_fmac_f32_e32 v182, v241, v141
	v_fmac_f32_e32 v186, v247, v143
	v_fmac_f32_e32 v183, v241, v36
	v_fmac_f32_e32 v187, v247, v32
	v_fmac_f32_e32 v184, v241, v37
	v_fmac_f32_e32 v188, v247, v33
	v_fmac_f32_e32 v185, v241, v38
	v_fmac_f32_e32 v189, v247, v34
	v_exp_f32_e32 v148, v182
	v_exp_f32_e32 v149, v183
	v_exp_f32_e32 v150, v184
	v_exp_f32_e32 v151, v185
	v_pk_mul_f32 v[182:183], v[182:183], v[186:187]
	v_pk_mul_f32 v[184:185], v[184:185], v[188:189]
	v_pk_add_f32 v[148:149], v[148:149], v[162:163]
	v_pk_add_f32 v[150:151], v[150:151], v[162:163]
	v_rcp_f32_e32 v148, v148
	v_rcp_f32_e32 v149, v149
	v_rcp_f32_e32 v150, v150
	v_rcp_f32_e32 v151, v151
	v_pk_mul_f32 v[164:165], v[164:165], v[144:145]
	v_pk_mul_f32 v[166:167], v[166:167], v[146:147]
	v_pk_mul_f32 v[182:183], v[182:183], v[148:149]
	v_pk_mul_f32 v[184:185], v[184:185], v[150:151]
	v_cvt_pk_bf16_f32 v152, v164, v182
	v_cvt_pk_bf16_f32 v153, v165, v183
	v_cvt_pk_bf16_f32 v154, v166, v184
	v_cvt_pk_bf16_f32 v155, v167, v185
	global_store_dword v157, v152, s[76:77]
	s_add_u32 s76, s76, 0x1600
	s_addc_u32 s77, s77, 0
	global_store_dword v157, v153, s[76:77]
	s_add_u32 s76, s76, 0x1600
	s_addc_u32 s77, s77, 0
	global_store_dword v157, v154, s[76:77]
	s_add_u32 s76, s76, 0x1600
	s_addc_u32 s77, s77, 0
	global_store_dword v157, v155, s[76:77]
	s_add_u32 s76, s76, 0x11e00
	s_addc_u32 s77, s77, 0
	ds_bpermute_b32 v220, v158, v2
	ds_bpermute_b32 v221, v158, v3
	ds_bpermute_b32 v222, v158, v6
	ds_bpermute_b32 v223, v158, v7
	ds_bpermute_b32 v224, v158, v14
	ds_bpermute_b32 v225, v158, v15
	s_waitcnt lgkmcnt(13)
	ds_bpermute_b32 v226, v158, v10
	s_waitcnt lgkmcnt(13)
	ds_bpermute_b32 v227, v158, v11
	s_waitcnt lgkmcnt(12)
	v_cndmask_b32_e64 v140, v212, v204, s[8:9]
	v_cndmask_b32_e64 v141, v213, v205, s[8:9]
	v_cndmask_b32_e64 v142, v214, v206, s[8:9]
	v_cndmask_b32_e64 v143, v215, v207, s[8:9]
	v_pk_fma_f32 v[164:165], v[238:239], v[140:141], v[250:251] op_sel_hi:[0,1,0]
	v_pk_fma_f32 v[168:169], v[244:245], v[142:143], v[252:253] op_sel_hi:[0,1,0]
	v_pk_fma_f32 v[166:167], v[238:239], v[28:29], v[250:251] op_sel_hi:[0,1,0]
	v_pk_fma_f32 v[170:171], v[244:245], v[24:25], v[252:253] op_sel_hi:[0,1,0]
	v_pk_fma_f32 v[164:165], v[242:243], v[28:29], v[164:165] op_sel_hi:[0,1,1]
	v_pk_fma_f32 v[168:169], v[248:249], v[24:25], v[168:169] op_sel_hi:[0,1,1]
	v_pk_fma_f32 v[166:167], v[242:243], v[30:31], v[166:167] op_sel_hi:[0,1,1]
	v_pk_fma_f32 v[170:171], v[248:249], v[26:27], v[170:171] op_sel_hi:[0,1,1]
	v_fmac_f32_e32 v164, v240, v141
	v_fmac_f32_e32 v168, v246, v143
	v_fmac_f32_e32 v165, v240, v28
	v_fmac_f32_e32 v169, v246, v24
	v_fmac_f32_e32 v166, v240, v29
	v_fmac_f32_e32 v170, v246, v25
	v_fmac_f32_e32 v167, v240, v30
	v_fmac_f32_e32 v171, v246, v26
	v_exp_f32_e32 v144, v164
	v_exp_f32_e32 v145, v165
	v_exp_f32_e32 v146, v166
	v_exp_f32_e32 v147, v167
	v_pk_mul_f32 v[164:165], v[164:165], v[168:169]
	v_pk_mul_f32 v[166:167], v[166:167], v[170:171]
	v_pk_add_f32 v[144:145], v[144:145], v[162:163]
	v_pk_add_f32 v[146:147], v[146:147], v[162:163]
	v_rcp_f32_e32 v144, v144
	v_rcp_f32_e32 v145, v145
	v_rcp_f32_e32 v146, v146
	v_rcp_f32_e32 v147, v147
	s_waitcnt lgkmcnt(8)
; #define PG8_LAS __attribute__((address_space(3)))
;     __device__ __forceinline__ void operator()(const f32x4 (&acc)[2][2][4][2], const Unit& u, int wr, int wc, int fr, int fq) const {
;     ...
;                 float o[2][4];
; #pragma unroll
;                 for (int n = 0; n < 2; ++n) {
;                     const f32x4 Xa = acc[ai][0][m][n], Xb = acc[ai][1][m][n];
;                     float da2, da3, db2, db3;
;                     if (m > 0) { const bool t = (fq == 3); da2 = t ? acc[ai][0][m > 0 ? m - 1 : 0][n][2] : Xa[2]; da3 = t ? acc[ai][0][m > 0 ? m - 1 : 0][n][3] : Xa[3];
;                                  db2 = t ? acc[ai][1][m > 0 ? m - 1 : 0][n][2] : Xb[2]; db3 = t ? acc[ai][1][m > 0 ? m - 1 : 0][n][3] : Xb[3]; }
;                     else { da2 = Xa[2]; da3 = Xa[3]; db2 = Xb[2]; db3 = Xb[3]; }
;                     float Ha2 = __builtin_bit_cast(float, __builtin_amdgcn_ds_bpermute(src, __builtin_bit_cast(int, da2)));
;                     float Ha3 = __builtin_bit_cast(float, __builtin_amdgcn_ds_bpermute(src, __builtin_bit_cast(int, da3)));
;                     float Hb2 = __builtin_bit_cast(float, __builtin_amdgcn_ds_bpermute(src, __builtin_bit_cast(int, db2)));
;                     float Hb3 = __builtin_bit_cast(float, __builtin_amdgcn_ds_bpermute(src, __builtin_bit_cast(int, db3)));
;                     if (m == 0) {
;                         float h2a = 0.f, h3a = 0.f, h2b = 0.f, h3b = 0.f;
;                         if (blk > 0) { const PG8_LAS float* hp = halo + ((((blk - 1) * 4 + wc) * 2 + 0) * 2 + n) * 32 + fr; h2a = hp[0]; h3a = hp[16]; h2b = hp[64]; h3b = hp[80]; }
;                         if (fq == 0) { Ha2 = h2a; Ha3 = h3a; Hb2 = h2b; Hb3 = h3b; }
;                     }
;                     const f32x2_t W0 = {wa[n][0], wb[n][0]}, W1 = {wa[n][1], wb[n][1]}, W2 = {wa[n][2], wb[n][2]}, B2 = {ba[n], bb[n]};
;                     const f32x2_t H2 = {Ha2, Hb2}, H3 = {Ha3, Hb3}, X0 = {Xa[0], Xb[0]}, X1 = {Xa[1], Xb[1]}, X2 = {Xa[2], Xb[2]}, X3 = {Xa[3], Xb[3]};
;                     const f32x2_t y0 = B2 + W0 * H2 + W1 * H3 + W2 * X0, y1 = B2 + W0 * H3 + W1 * X0 + W2 * X1, y2 = B2 + W0 * X0 + W1 * X1 + W2 * X2, y3 = B2 + W0 * X1 + W1 * X2 + W2 * X3;
;                     const float ya0 = y0[0], yb0 = y0[1], ya1 = y1[0], yb1 = y1[1], ya2 = y2[0], yb2 = y2[1], ya3 = y3[0], yb3 = y3[1];
	v_cndmask_b32_e64 v140, v216, v208, s[8:9]
	v_cndmask_b32_e64 v141, v217, v209, s[8:9]
	v_cndmask_b32_e64 v142, v218, v210, s[8:9]
	v_cndmask_b32_e64 v143, v219, v211, s[8:9]
	v_pk_fma_f32 v[182:183], v[238:239], v[140:141], v[250:251] op_sel:[1,0,1] op_sel_hi:[1,1,1]
	v_pk_fma_f32 v[186:187], v[244:245], v[142:143], v[252:253] op_sel:[1,0,1] op_sel_hi:[1,1,1]
	v_pk_fma_f32 v[184:185], v[238:239], v[20:21], v[250:251] op_sel:[1,0,1] op_sel_hi:[1,1,1]
	v_pk_fma_f32 v[188:189], v[244:245], v[16:17], v[252:253] op_sel:[1,0,1] op_sel_hi:[1,1,1]
	v_pk_fma_f32 v[182:183], v[242:243], v[20:21], v[182:183] op_sel:[1,0,0] op_sel_hi:[1,1,1]
	v_pk_fma_f32 v[186:187], v[248:249], v[16:17], v[186:187] op_sel:[1,0,0] op_sel_hi:[1,1,1]
	v_pk_fma_f32 v[184:185], v[242:243], v[22:23], v[184:185] op_sel:[1,0,0] op_sel_hi:[1,1,1]
	v_pk_fma_f32 v[188:189], v[248:249], v[18:19], v[188:189] op_sel:[1,0,0] op_sel_hi:[1,1,1]
	v_fmac_f32_e32 v182, v241, v141
	v_fmac_f32_e32 v186, v247, v143
	v_fmac_f32_e32 v183, v241, v20
	v_fmac_f32_e32 v187, v247, v16
	v_fmac_f32_e32 v184, v241, v21
	v_fmac_f32_e32 v188, v247, v17
	v_fmac_f32_e32 v185, v241, v22
	v_fmac_f32_e32 v189, v247, v18
	v_exp_f32_e32 v148, v182
	v_exp_f32_e32 v149, v183
	v_exp_f32_e32 v150, v184
	v_exp_f32_e32 v151, v185
	v_pk_mul_f32 v[182:183], v[182:183], v[186:187]
	v_pk_mul_f32 v[184:185], v[184:185], v[188:189]
	v_pk_add_f32 v[148:149], v[148:149], v[162:163]
	v_pk_add_f32 v[150:151], v[150:151], v[162:163]
	v_rcp_f32_e32 v148, v148
	v_rcp_f32_e32 v149, v149
	v_rcp_f32_e32 v150, v150
	v_rcp_f32_e32 v151, v151
	v_pk_mul_f32 v[164:165], v[164:165], v[144:145]
	v_pk_mul_f32 v[166:167], v[166:167], v[146:147]
	v_pk_mul_f32 v[182:183], v[182:183], v[148:149]
	v_pk_mul_f32 v[184:185], v[184:185], v[150:151]
	v_cvt_pk_bf16_f32 v152, v164, v182
	v_cvt_pk_bf16_f32 v153, v165, v183
	v_cvt_pk_bf16_f32 v154, v166, v184
	v_cvt_pk_bf16_f32 v155, v167, v185
	global_store_dword v157, v152, s[76:77]
	s_add_u32 s76, s76, 0x1600
	s_addc_u32 s77, s77, 0
	global_store_dword v157, v153, s[76:77]
	s_add_u32 s76, s76, 0x1600
	s_addc_u32 s77, s77, 0
	global_store_dword v157, v154, s[76:77]
	s_add_u32 s76, s76, 0x1600
	s_addc_u32 s77, s77, 0
	global_store_dword v157, v155, s[76:77]
	s_add_u32 s76, s76, 0x11e00
	s_addc_u32 s77, s77, 0
	s_waitcnt lgkmcnt(4)
	v_cndmask_b32_e64 v140, v220, v212, s[8:9]
	v_cndmask_b32_e64 v141, v221, v213, s[8:9]
	v_cndmask_b32_e64 v142, v222, v214, s[8:9]
	v_cndmask_b32_e64 v143, v223, v215, s[8:9]
	v_pk_fma_f32 v[164:165], v[238:239], v[140:141], v[250:251] op_sel_hi:[0,1,0]
	v_pk_fma_f32 v[168:169], v[244:245], v[142:143], v[252:253] op_sel_hi:[0,1,0]
	v_pk_fma_f32 v[166:167], v[238:239], v[0:1], v[250:251] op_sel_hi:[0,1,0]
	v_pk_fma_f32 v[170:171], v[244:245], v[4:5], v[252:253] op_sel_hi:[0,1,0]
	v_pk_fma_f32 v[164:165], v[242:243], v[0:1], v[164:165] op_sel_hi:[0,1,1]
	v_pk_fma_f32 v[168:169], v[248:249], v[4:5], v[168:169] op_sel_hi:[0,1,1]
	v_pk_fma_f32 v[166:167], v[242:243], v[2:3], v[166:167] op_sel_hi:[0,1,1]
	v_pk_fma_f32 v[170:171], v[248:249], v[6:7], v[170:171] op_sel_hi:[0,1,1]
	v_fmac_f32_e32 v164, v240, v141
	v_fmac_f32_e32 v168, v246, v143
	v_fmac_f32_e32 v165, v240, v0
	v_fmac_f32_e32 v169, v246, v4
	v_fmac_f32_e32 v166, v240, v1
	v_fmac_f32_e32 v170, v246, v5
	v_fmac_f32_e32 v167, v240, v2
	v_fmac_f32_e32 v171, v246, v6
	v_exp_f32_e32 v144, v164
	v_exp_f32_e32 v145, v165
	v_exp_f32_e32 v146, v166
	v_exp_f32_e32 v147, v167
	v_pk_mul_f32 v[164:165], v[164:165], v[168:169]
	v_pk_mul_f32 v[166:167], v[166:167], v[170:171]
	v_pk_add_f32 v[144:145], v[144:145], v[162:163]
	v_pk_add_f32 v[146:147], v[146:147], v[162:163]
	v_rcp_f32_e32 v144, v144
	v_rcp_f32_e32 v145, v145
	v_rcp_f32_e32 v146, v146
	v_rcp_f32_e32 v147, v147
	s_waitcnt lgkmcnt(0)
	v_cndmask_b32_e64 v140, v224, v216, s[8:9]
	v_cndmask_b32_e64 v141, v225, v217, s[8:9]
	v_cndmask_b32_e64 v142, v226, v218, s[8:9]
	v_cndmask_b32_e64 v143, v227, v219, s[8:9]
	v_pk_fma_f32 v[182:183], v[238:239], v[140:141], v[250:251] op_sel:[1,0,1] op_sel_hi:[1,1,1]
	v_pk_fma_f32 v[186:187], v[244:245], v[142:143], v[252:253] op_sel:[1,0,1] op_sel_hi:[1,1,1]
	v_pk_fma_f32 v[184:185], v[238:239], v[12:13], v[250:251] op_sel:[1,0,1] op_sel_hi:[1,1,1]
	v_pk_fma_f32 v[188:189], v[244:245], v[8:9], v[252:253] op_sel:[1,0,1] op_sel_hi:[1,1,1]
	v_pk_fma_f32 v[182:183], v[242:243], v[12:13], v[182:183] op_sel:[1,0,0] op_sel_hi:[1,1,1]
	v_pk_fma_f32 v[186:187], v[248:249], v[8:9], v[186:187] op_sel:[1,0,0] op_sel_hi:[1,1,1]
	v_pk_fma_f32 v[184:185], v[242:243], v[14:15], v[184:185] op_sel:[1,0,0] op_sel_hi:[1,1,1]
	v_pk_fma_f32 v[188:189], v[248:249], v[10:11], v[188:189] op_sel:[1,0,0] op_sel_hi:[1,1,1]
	v_fmac_f32_e32 v182, v241, v141
	v_fmac_f32_e32 v186, v247, v143
	v_fmac_f32_e32 v183, v241, v12
	v_fmac_f32_e32 v187, v247, v8
	v_fmac_f32_e32 v184, v241, v13
	v_fmac_f32_e32 v188, v247, v9
	v_fmac_f32_e32 v185, v241, v14
	v_fmac_f32_e32 v189, v247, v10
	v_exp_f32_e32 v148, v182
	v_exp_f32_e32 v149, v183
	v_exp_f32_e32 v150, v184
	v_exp_f32_e32 v151, v185
	v_pk_mul_f32 v[182:183], v[182:183], v[186:187]
	v_pk_mul_f32 v[184:185], v[184:185], v[188:189]
	v_pk_add_f32 v[148:149], v[148:149], v[162:163]
	v_pk_add_f32 v[150:151], v[150:151], v[162:163]
	v_rcp_f32_e32 v148, v148
	v_rcp_f32_e32 v149, v149
	v_rcp_f32_e32 v150, v150
	v_rcp_f32_e32 v151, v151
	v_pk_mul_f32 v[164:165], v[164:165], v[144:145]
	v_pk_mul_f32 v[166:167], v[166:167], v[146:147]
	v_pk_mul_f32 v[182:183], v[182:183], v[148:149]
	v_pk_mul_f32 v[184:185], v[184:185], v[150:151]
	v_cvt_pk_bf16_f32 v152, v164, v182
	v_cvt_pk_bf16_f32 v153, v165, v183
	v_cvt_pk_bf16_f32 v154, v166, v184
	v_cvt_pk_bf16_f32 v155, v167, v185
	global_store_dword v157, v152, s[76:77]
	s_add_u32 s76, s76, 0x1600
	s_addc_u32 s77, s77, 0
	global_store_dword v157, v153, s[76:77]
	s_add_u32 s76, s76, 0x1600
	s_addc_u32 s77, s77, 0
	global_store_dword v157, v154, s[76:77]
	s_add_u32 s76, s76, 0x1600
	s_addc_u32 s77, s77, 0
	global_store_dword v157, v155, s[76:77]
	s_andn2_b64 vcc, exec, s[14:15]
	s_mov_b64 s[14:15], -1
	s_cbranch_vccnz .LBB0_882
	s_andn2_b64 vcc, exec, s[38:39]
	s_cbranch_vccnz .LBB0_881
	s_barrier
	s_branch .LBB0_881
